# added quad / neighbour / split-barrier waits poll back to back (no s_sleep between polls)
# speedup vs baseline: 1.0076x; 1.0076x over previous
; #define SEAM(k) do { if ((k) < 2) xcd_barrier(bar); else xcd_barrier(barg); } while (0)
; __global__ void __launch_bounds__(NWAVES * 64, 2) fwd(Args a) {
;     ...
;     SEAM(0);
.Lp1_spin:
	global_load_dword v244, v[242:243], off sc1
	s_waitcnt vmcnt(0)
	v_cmp_lt_u32_e32 vcc, v244, v241
	s_cbranch_vccz .Lp1_released
	s_add_i32 s13, s13, 1
	s_cmp_lt_u32 s13, 0x40000
	s_cbranch_scc1 .Lp1_spin

; #define SEAM(k) do { if ((k) < 2) xcd_barrier(bar); else xcd_barrier(barg); } while (0)
; __global__ void __launch_bounds__(NWAVES * 64, 2) fwd(Args a) {
;     ...
;     SEAM(4);
.Lq4_spin:
	global_load_dword v3, v1, s[4:5] sc1
	s_waitcnt vmcnt(0)
	v_cmp_gt_u32_e32 vcc, 4, v3
	s_cbranch_vccz .Lq4_ok
	s_add_i32 s7, s7, 1
	s_cmp_lt_u32 s7, 0x40000
	s_cbranch_scc1 .Lq4_spin

; #define SEAM(k) do { if ((k) < 2) xcd_barrier(bar); else xcd_barrier(barg); } while (0)
; __global__ void __launch_bounds__(NWAVES * 64, 2) fwd(Args a) {
;     ...
;     SEAM(5);
.Lq5a_spin:
	global_load_dword v3, v1, s[4:5] sc1
	s_waitcnt vmcnt(0)
	v_cmp_gt_u32_e32 vcc, 4, v3
	s_cbranch_vccz .Lq5a_ok
	s_add_i32 s9, s9, 1
	s_cmp_lt_u32 s9, 0x40000
	s_cbranch_scc1 .Lq5a_spin
